# P3 epilogue merge-gate loads marked nt (read-once stream, keeps MIX and weights in L2)
# baseline (speedup 1.0000x reference)
;     __device__ __forceinline__ void operator()(const f32x4 (&acc)[2][2][4][2], const Unit& u, int wr, int wc, int fr, int fq) const {
;         const int row0 = u.pm * BM + wr * 64 + fr, col0 = u.pn * BM + wc * 32 + 8 * fq, br = u.br;
; #pragma unroll
;         for (int ai = 0; ai < 2; ++ai) {
;             u32x4 gv[4][2], pv[4][2];
; #pragma unroll
;             for (int m = 0; m < 4; ++m)
; #pragma unroll
;                 for (int bj = 0; bj < 2; ++bj) { const int row = row0 + ai * HALF + m * 16, col = col0 + bj * HALF;
;                     gv[m][bj] = *(const u32x4*)(P + PB(8448 + br * 1024 + col) + (size_t)row * 64);
;                     if (br > 0) pv[m][bj] = *(const u32x4*)(MIX + (size_t)row * 1024 + col); else pv[m][bj] = (u32x4){0u, 0u, 0u, 0u}; }
.LBB0_398:
	s_lshl_b32 s6, s12, 8
	s_or_b32 s7, s6, s56
	s_lshl_b32 s6, s46, 10
	s_addk_i32 s6, 0x2100
	s_cmp_gt_i32 s46, 0
	v_lshl_add_u32 v214, s13, 8, v243
	s_cselect_b64 s[12:13], -1, 0
	s_cmp_lt_i32 s46, 1
	v_or_b32_e32 v212, s7, v244
	v_bitop3_b32 v120, s7, 56, v244 bitop3:0xc8
	s_cselect_b64 s[48:49], -1, 0
	s_add_i32 s7, s7, s6
	v_lshlrev_b32_e32 v192, 1, v120
	v_ashrrev_i32_e32 v215, 31, v214
	s_ashr_i32 s46, s7, 6
	v_lshl_add_u64 v[216:217], s[10:11], 0, v[192:193]
	v_lshlrev_b64 v[120:121], 7, v[214:215]
	s_ashr_i32 s47, s46, 31
	v_lshl_add_u64 v[120:121], v[216:217], 0, v[120:121]
	v_lshlrev_b64 v[122:123], 11, v[214:215]
	s_lshl_b64 s[60:61], s[46:47], 21
	v_lshl_add_u64 v[226:227], s[18:19], 0, v[122:123]
	v_lshl_add_u64 v[122:123], v[120:121], 0, s[60:61]
	global_load_dwordx4 v[188:191], v[122:123], off nt
	s_and_b64 vcc, exec, s[48:49]
	v_ashrrev_i32_e32 v213, 31, v212
	s_cbranch_vccnz .LBB0_400
	v_lshl_add_u64 v[122:123], v[212:213], 1, v[226:227]
	global_load_dwordx4 v[184:187], v[122:123], off nt
	s_branch .LBB0_401

;     __device__ __forceinline__ void operator()(const f32x4 (&acc)[2][2][4][2], const Unit& u, int wr, int wc, int fr, int fq) const {
;     ...
;             u32x4 gv[4][2], pv[4][2];
; #pragma unroll
;             for (int m = 0; m < 4; ++m)
; #pragma unroll
;                 for (int bj = 0; bj < 2; ++bj) { const int row = row0 + ai * HALF + m * 16, col = col0 + bj * HALF;
;                     gv[m][bj] = *(const u32x4*)(P + PB(8448 + br * 1024 + col) + (size_t)row * 64);
;                     if (br > 0) pv[m][bj] = *(const u32x4*)(MIX + (size_t)row * 1024 + col); else pv[m][bj] = (u32x4){0u, 0u, 0u, 0u}; }
.LBB0_401:
	v_add_u32_e32 v122, s6, v212
	v_add_u32_e32 v122, 0x80, v122
	v_ashrrev_i32_e32 v122, 6, v122
	v_ashrrev_i32_e32 v123, 31, v122
	v_lshlrev_b64 v[218:219], 21, v[122:123]
	v_lshl_add_u64 v[120:121], v[120:121], 0, v[218:219]
	global_load_dwordx4 v[180:183], v[120:121], off nt
	v_cndmask_b32_e64 v120, 0, 1, s[12:13]
	v_mov_b32_e32 v168, 0
	v_cmp_ne_u32_e64 s[6:7], 1, v120
	s_andn2_b64 vcc, exec, s[12:13]
	v_mov_b32_e32 v176, 0
	v_mov_b32_e32 v177, 0
	v_mov_b32_e32 v178, 0
	v_mov_b32_e32 v179, 0
	s_cbranch_vccnz .LBB0_403
	v_lshl_add_u64 v[120:121], v[212:213], 1, v[226:227]
	global_load_dwordx4 v[176:179], v[120:121], off offset:256
.LBB0_403:
	v_or_b32_e32 v122, 16, v214
	v_ashrrev_i32_e32 v123, 31, v122
	v_lshlrev_b64 v[120:121], 7, v[122:123]
	v_lshl_add_u64 v[120:121], v[216:217], 0, v[120:121]
	v_lshl_add_u64 v[124:125], v[120:121], 0, s[60:61]
	global_load_dwordx4 v[172:175], v[124:125], off nt
	v_lshlrev_b64 v[122:123], 11, v[122:123]
	v_lshl_add_u64 v[224:225], s[18:19], 0, v[122:123]
	s_and_b64 vcc, exec, s[6:7]
	v_mov_b32_e32 v169, 0
	v_mov_b32_e32 v170, 0
	v_mov_b32_e32 v171, 0
	s_cbranch_vccnz .LBB0_405
	v_lshl_add_u64 v[122:123], v[212:213], 1, v[224:225]
	global_load_dwordx4 v[168:171], v[122:123], off
.LBB0_405:
	v_lshl_add_u64 v[120:121], v[120:121], 0, v[218:219]
	global_load_dwordx4 v[164:167], v[120:121], off nt
	v_mov_b32_e32 v152, 0
	s_and_b64 vcc, exec, s[6:7]
	v_mov_b32_e32 v160, 0
	v_mov_b32_e32 v161, 0
	v_mov_b32_e32 v162, 0
	v_mov_b32_e32 v163, 0
	s_cbranch_vccnz .LBB0_407
	v_lshl_add_u64 v[120:121], v[212:213], 1, v[224:225]
	global_load_dwordx4 v[160:163], v[120:121], off offset:256
.LBB0_407:
	v_or_b32_e32 v122, 32, v214
	v_ashrrev_i32_e32 v123, 31, v122
	v_lshlrev_b64 v[120:121], 7, v[122:123]
	v_lshl_add_u64 v[120:121], v[216:217], 0, v[120:121]
	v_lshl_add_u64 v[124:125], v[120:121], 0, s[60:61]
	global_load_dwordx4 v[156:159], v[124:125], off nt
	v_lshlrev_b64 v[122:123], 11, v[122:123]
	v_lshl_add_u64 v[222:223], s[18:19], 0, v[122:123]
	s_and_b64 vcc, exec, s[6:7]
	v_mov_b32_e32 v153, 0
	v_mov_b32_e32 v154, 0
	v_mov_b32_e32 v155, 0
	s_cbranch_vccnz .LBB0_409
	v_lshl_add_u64 v[122:123], v[212:213], 1, v[222:223]
	global_load_dwordx4 v[152:155], v[122:123], off
.LBB0_409:
	v_lshl_add_u64 v[120:121], v[120:121], 0, v[218:219]
	global_load_dwordx4 v[148:151], v[120:121], off nt
	v_mov_b32_e32 v132, 0
	s_and_b64 vcc, exec, s[6:7]
	v_mov_b32_e32 v144, 0
	v_mov_b32_e32 v145, 0
	v_mov_b32_e32 v146, 0
	v_mov_b32_e32 v147, 0
	s_cbranch_vccnz .LBB0_411
	v_lshl_add_u64 v[120:121], v[212:213], 1, v[222:223]
	global_load_dwordx4 v[144:147], v[120:121], off offset:256
.LBB0_411:
	v_or_b32_e32 v122, 48, v214
	v_ashrrev_i32_e32 v123, 31, v122
	v_lshlrev_b64 v[120:121], 7, v[122:123]
	v_lshl_add_u64 v[120:121], v[216:217], 0, v[120:121]
	v_lshl_add_u64 v[124:125], v[120:121], 0, s[60:61]
	global_load_dwordx4 v[136:139], v[124:125], off nt
	v_lshlrev_b64 v[122:123], 11, v[122:123]
	v_lshl_add_u64 v[220:221], s[18:19], 0, v[122:123]
	s_and_b64 vcc, exec, s[6:7]
	v_mov_b32_e32 v133, 0
	v_mov_b32_e32 v134, 0
	v_mov_b32_e32 v135, 0
	s_cbranch_vccnz .LBB0_413
	v_lshl_add_u64 v[122:123], v[212:213], 1, v[220:221]
	global_load_dwordx4 v[132:135], v[122:123], off
.LBB0_413:
	v_lshl_add_u64 v[120:121], v[120:121], 0, v[218:219]
	global_load_dwordx4 v[124:127], v[120:121], off nt
	s_andn2_b64 vcc, exec, s[48:49]
	s_mov_b64 s[12:13], -1
	s_cbranch_vccnz .LBB0_415
	s_mov_b64 s[12:13], 0

; __device__ __forceinline__ unsigned cvt_pk_bf16(float lo, float hi) { unsigned r; asm volatile("v_cvt_pk_bf16_f32 %0, %1, %2" : "=v"(r) : "v"(lo), "v"(hi)); return r; }
; __device__ __forceinline__ float bf_lo(unsigned w) { return __uint_as_float(w << 16); }
; __device__ __forceinline__ float bf_hi(unsigned w) { return __uint_as_float(w & 0xffff0000u); }
; __device__ __forceinline__ float sigmoidf_(float x) { return __builtin_amdgcn_rcpf(1.0f + __builtin_amdgcn_exp2f(-x * 1.4426950408889634f)); }
;     __device__ __forceinline__ void operator()(const f32x4 (&acc)[2][2][4][2], const Unit& u, int wr, int wc, int fr, int fq) const {
;     ...
;             for (int m = 0; m < 4; ++m)
; #pragma unroll
;                 for (int bj = 0; bj < 2; ++bj) { const int row = row0 + ai * HALF + m * 16, col = col0 + bj * HALF;
;                     gv[m][bj] = *(const u32x4*)(P + PB(8448 + br * 1024 + col) + (size_t)row * 64);
;                     if (br > 0) pv[m][bj] = *(const u32x4*)(MIX + (size_t)row * 1024 + col); else pv[m][bj] = (u32x4){0u, 0u, 0u, 0u}; }
;             asm volatile("" ::: "memory");
; #pragma unroll
;             for (int m = 0; m < 4; ++m) { const int row = row0 + ai * HALF + m * 16;
; #pragma unroll
;                 for (int bj = 0; bj < 2; ++bj) { const int col = col0 + bj * HALF;
;                     const u32x4 g = gv[m][bj];
;                     bf16_t* mp = MIX + (size_t)row * 1024 + col;
;                     f32x4 v0 = acc[ai][bj][m][0], v1 = acc[ai][bj][m][1];
;                     v0[0] *= sigmoidf_(bf_lo(g.x)); v0[1] *= sigmoidf_(bf_hi(g.x)); v0[2] *= sigmoidf_(bf_lo(g.y)); v0[3] *= sigmoidf_(bf_hi(g.y));
;                     v1[0] *= sigmoidf_(bf_lo(g.z)); v1[1] *= sigmoidf_(bf_hi(g.z)); v1[2] *= sigmoidf_(bf_lo(g.w)); v1[3] *= sigmoidf_(bf_hi(g.w));
;                     if (br > 0) { const u32x4 p = pv[m][bj];
;                         v0[0] += bf_lo(p.x); v0[1] += bf_hi(p.x); v0[2] += bf_lo(p.y); v0[3] += bf_hi(p.y); v1[0] += bf_lo(p.z); v1[1] += bf_hi(p.z); v1[2] += bf_lo(p.w); v1[3] += bf_hi(p.w); }
;                     u32x4 w; w.x = cvt_pk_bf16(v0[0], v0[1]); w.y = cvt_pk_bf16(v0[2], v0[3]); w.z = cvt_pk_bf16(v1[0], v1[1]); w.w = cvt_pk_bf16(v1[2], v1[3]);
;                     *(u32x4*)mp = w; } }
.LBB0_433:
	v_cvt_pk_bf16_f32 v68, v68, v69
	v_cvt_pk_bf16_f32 v69, v70, v71
	v_cvt_pk_bf16_f32 v70, v64, v65
	s_nop 0
	v_cvt_pk_bf16_f32 v71, v66, v67
	v_add_u32_e32 v66, 0x80, v214
	v_ashrrev_i32_e32 v67, 31, v66
	v_lshlrev_b64 v[64:65], 7, v[66:67]
	global_store_dwordx4 v[72:73], v[68:71], off offset:256
	v_lshl_add_u64 v[64:65], v[216:217], 0, v[64:65]
	v_lshlrev_b64 v[66:67], 11, v[66:67]
	v_lshl_add_u64 v[68:69], v[64:65], 0, s[60:61]
	global_load_dwordx4 v[124:127], v[68:69], off nt
	v_lshl_add_u64 v[66:67], s[18:19], 0, v[66:67]
	v_mov_b32_e32 v112, 0
	s_and_b64 vcc, exec, s[6:7]
	v_lshl_add_u64 v[134:135], v[212:213], 1, v[66:67]
	v_mov_b32_e32 v120, 0
	v_mov_b32_e32 v121, 0
	v_mov_b32_e32 v122, 0
	v_mov_b32_e32 v123, 0
	s_cbranch_vccnz .LBB0_435
	global_load_dwordx4 v[120:123], v[134:135], off
.LBB0_435:
	v_lshl_add_u64 v[64:65], v[64:65], 0, v[218:219]
	global_load_dwordx4 v[116:119], v[64:65], off nt
	s_and_b64 vcc, exec, s[6:7]
	v_mov_b32_e32 v113, 0
	v_mov_b32_e32 v114, 0
	v_mov_b32_e32 v115, 0
	s_cbranch_vccnz .LBB0_437
	global_load_dwordx4 v[112:115], v[134:135], off offset:256
.LBB0_437:
	v_add_u32_e32 v66, 0x90, v214
	v_ashrrev_i32_e32 v67, 31, v66
	v_lshlrev_b64 v[64:65], 7, v[66:67]
	v_lshl_add_u64 v[64:65], v[216:217], 0, v[64:65]
	v_lshl_add_u64 v[68:69], v[64:65], 0, s[60:61]
	global_load_dwordx4 v[108:111], v[68:69], off nt
	v_lshlrev_b64 v[66:67], 11, v[66:67]
	v_lshl_add_u64 v[66:67], s[18:19], 0, v[66:67]
	v_mov_b32_e32 v96, 0
	s_and_b64 vcc, exec, s[6:7]
	v_lshl_add_u64 v[132:133], v[212:213], 1, v[66:67]
	v_mov_b32_e32 v104, 0
	v_mov_b32_e32 v105, 0
	v_mov_b32_e32 v106, 0
	v_mov_b32_e32 v107, 0
	s_cbranch_vccnz .LBB0_439
	global_load_dwordx4 v[104:107], v[132:133], off
.LBB0_439:
	v_lshl_add_u64 v[64:65], v[64:65], 0, v[218:219]
	global_load_dwordx4 v[100:103], v[64:65], off nt
	s_and_b64 vcc, exec, s[6:7]
	v_mov_b32_e32 v97, 0
	v_mov_b32_e32 v98, 0
	v_mov_b32_e32 v99, 0
	s_cbranch_vccnz .LBB0_441
	global_load_dwordx4 v[96:99], v[132:133], off offset:256
.LBB0_441:
	v_add_u32_e32 v66, 0xa0, v214
	v_ashrrev_i32_e32 v67, 31, v66
	v_lshlrev_b64 v[64:65], 7, v[66:67]
	v_lshl_add_u64 v[64:65], v[216:217], 0, v[64:65]
	v_lshl_add_u64 v[68:69], v[64:65], 0, s[60:61]
	global_load_dwordx4 v[92:95], v[68:69], off nt
	v_lshlrev_b64 v[66:67], 11, v[66:67]
	v_lshl_add_u64 v[66:67], s[18:19], 0, v[66:67]
	v_mov_b32_e32 v80, 0
	s_and_b64 vcc, exec, s[6:7]
	v_lshl_add_u64 v[130:131], v[212:213], 1, v[66:67]
	v_mov_b32_e32 v88, 0
	v_mov_b32_e32 v89, 0
	v_mov_b32_e32 v90, 0
	v_mov_b32_e32 v91, 0
	s_cbranch_vccnz .LBB0_443
	global_load_dwordx4 v[88:91], v[130:131], off
.LBB0_443:
	v_lshl_add_u64 v[64:65], v[64:65], 0, v[218:219]
	global_load_dwordx4 v[84:87], v[64:65], off nt
	s_and_b64 vcc, exec, s[6:7]
	v_mov_b32_e32 v81, 0
	v_mov_b32_e32 v82, 0
	v_mov_b32_e32 v83, 0
	s_cbranch_vccnz .LBB0_445
	global_load_dwordx4 v[80:83], v[130:131], off offset:256
.LBB0_445:
	v_add_u32_e32 v64, 0xb0, v214
	v_ashrrev_i32_e32 v65, 31, v64
	v_lshlrev_b64 v[66:67], 7, v[64:65]
	v_lshl_add_u64 v[66:67], v[216:217], 0, v[66:67]
	v_lshl_add_u64 v[68:69], v[66:67], 0, s[60:61]
	global_load_dwordx4 v[76:79], v[68:69], off nt
	v_lshlrev_b64 v[64:65], 11, v[64:65]
	v_lshl_add_u64 v[68:69], s[18:19], 0, v[64:65]
	v_mov_b32_e32 v64, 0
	s_and_b64 vcc, exec, s[6:7]
	v_lshl_add_u64 v[128:129], v[212:213], 1, v[68:69]
	v_mov_b32_e32 v72, 0
	v_mov_b32_e32 v73, 0
	v_mov_b32_e32 v74, 0
	v_mov_b32_e32 v75, 0
	s_cbranch_vccnz .LBB0_447
	global_load_dwordx4 v[72:75], v[128:129], off
.LBB0_447:
	v_lshl_add_u64 v[66:67], v[66:67], 0, v[218:219]
	global_load_dwordx4 v[68:71], v[66:67], off nt
	s_and_b64 vcc, exec, s[6:7]
	v_mov_b32_e32 v65, 0
	v_mov_b32_e32 v66, 0
	v_mov_b32_e32 v67, 0
	s_cbranch_vccnz .LBB0_449
	global_load_dwordx4 v[64:67], v[128:129], off offset:256
